# HGRN items no longer run at raised wave priority (HGRN chain has slack now that phase 2 is DSA-throughput-bound)
# baseline (speedup 1.0000x reference)
.LBB0_173:
	s_or_b64 exec, exec, s[42:43]
	s_waitcnt lgkmcnt(0)
	s_barrier
	ds_read_b32 v2, v126
	s_mov_b64 s[42:43], -1
	s_waitcnt lgkmcnt(0)
	v_cmp_lt_i32_e32 vcc, 31, v2
	v_readfirstlane_b32 s45, v2
	s_cbranch_vccnz .LBB0_168
	s_setprio 0
	v_and_b32_e32 v236, 3, v147
	v_lshlrev_b32_e32 v236, 7, v236
	v_add_u32_e32 v236, 0x11e00, v236
	global_load_dwordx4 v[240:243], v[128:129], off
	global_load_dwordx4 v[244:247], v[128:129], off offset:16
	global_load_dwordx4 v[248:251], v[128:129], off offset:32
	s_waitcnt vmcnt(0)
	ds_write_b128 v236, v[240:243]
	ds_write_b128 v236, v[244:247] offset:16
	ds_write_b128 v236, v[248:251] offset:32
	s_waitcnt lgkmcnt(0)
	global_load_dwordx4 v[240:243], v[128:129], off offset:48
	global_load_dwordx4 v[244:247], v[128:129], off offset:64
	global_load_dwordx4 v[248:251], v[128:129], off offset:80
	s_waitcnt vmcnt(0)
	ds_write_b128 v236, v[240:243] offset:48
	ds_write_b128 v236, v[244:247] offset:64
	ds_write_b128 v236, v[248:251] offset:80
	s_waitcnt lgkmcnt(0)
	global_load_dwordx4 v[240:243], v[128:129], off offset:96
	global_load_dwordx4 v[244:247], v[128:129], off offset:112
	s_waitcnt vmcnt(0)
	ds_write_b128 v236, v[240:243] offset:96
	ds_write_b128 v236, v[244:247] offset:112
	s_waitcnt lgkmcnt(0)
	v_readfirstlane_b32 s44, v147
	s_lshr_b32 s44, s44, 1
	s_ashr_i32 s42, s45, 2
	s_and_b32 s44, s44, 0x7fffffe0
	s_ashr_i32 s43, s42, 31
	v_or_b32_e32 v2, s44, v149
	v_cmp_lt_i32_e32 vcc, v166, v167
	s_and_b32 s45, s45, 3
	v_mul_lo_u32 v2, v2, s3
	v_cndmask_b32_e32 v3, v165, v166, vcc
	v_cmp_lt_i32_e32 vcc, v168, v167
	s_lshl_b64 s[46:47], s[42:43], 22
	s_lshl_b32 s51, s45, 8
	s_lshl_b64 s[42:43], s[42:43], 23
	s_lshl_b32 s45, s45, 9
	v_or_b32_e32 v170, v153, v2
	v_mov_b32_e32 v2, 0
	v_lshlrev_b32_e32 v172, 2, v3
	v_cndmask_b32_e32 v3, v165, v168, vcc
	s_or_b32 s46, s46, s51
	s_or_b32 s76, s42, s45
	s_mov_b32 s77, s43
	s_or_b32 s42, s42, s51
	v_lshl_add_u32 v171, s44, 2, v156
	s_mov_b32 s44, 64
	v_lshlrev_b32_e32 v173, 2, v3
	v_lshl_add_u64 v[138:139], s[46:47], 0, v[130:131]
	v_lshl_add_u64 v[140:141], s[76:77], 0, v[132:133]
	v_lshl_add_u64 v[142:143], s[46:47], 0, v[134:135]
	v_lshl_add_u64 v[144:145], s[42:43], 0, v[136:137]
	v_add_u32_e32 v174, v170, v153
	v_mov_b32_e32 v3, v2
	v_mov_b32_e32 v4, v2
	v_mov_b32_e32 v5, v2
	v_mov_b32_e32 v6, v2
	v_mov_b32_e32 v7, v2
	v_mov_b32_e32 v8, v2
	v_mov_b32_e32 v9, v2
	v_mov_b32_e32 v10, v2
	v_mov_b32_e32 v11, v2
	v_mov_b32_e32 v12, v2
	v_mov_b32_e32 v13, v2
	v_mov_b32_e32 v14, v2
	v_mov_b32_e32 v15, v2
	v_mov_b32_e32 v16, v2
	v_mov_b32_e32 v17, v2
	v_mov_b32_e32 v18, v2
	v_mov_b32_e32 v19, v2
	v_mov_b32_e32 v20, v2
	v_mov_b32_e32 v21, v2
	v_mov_b32_e32 v22, v2
	v_mov_b32_e32 v23, v2
	v_mov_b32_e32 v24, v2
	v_mov_b32_e32 v25, v2
	v_mov_b32_e32 v26, v2
	v_mov_b32_e32 v27, v2
	v_mov_b32_e32 v28, v2
	v_mov_b32_e32 v29, v2
	v_mov_b32_e32 v30, v2
	v_mov_b32_e32 v31, v2
	v_mov_b32_e32 v32, v2
	v_mov_b32_e32 v33, v2
	v_mov_b32_e32 v34, v2
	v_mov_b32_e32 v35, v2
	v_mov_b32_e32 v36, v2
	v_mov_b32_e32 v37, v2
	v_mov_b32_e32 v38, v2
	v_mov_b32_e32 v39, v2
	v_mov_b32_e32 v40, v2
	v_mov_b32_e32 v41, v2
	v_mov_b32_e32 v42, v2
	v_mov_b32_e32 v43, v2
	v_mov_b32_e32 v44, v2
	v_mov_b32_e32 v45, v2
	v_mov_b32_e32 v46, v2
	v_mov_b32_e32 v47, v2
	v_mov_b32_e32 v48, v2
	v_mov_b32_e32 v49, v2
	v_mov_b32_e32 v50, v2
	v_mov_b32_e32 v51, v2
	v_mov_b32_e32 v52, v2
	v_mov_b32_e32 v53, v2
	v_mov_b32_e32 v54, v2
	v_mov_b32_e32 v55, v2
	v_mov_b32_e32 v56, v2
	v_mov_b32_e32 v57, v2
	v_mov_b32_e32 v58, v2
	v_mov_b32_e32 v59, v2
	v_mov_b32_e32 v60, v2
	v_mov_b32_e32 v61, v2
	v_mov_b32_e32 v62, v2
	v_mov_b32_e32 v63, v2
	v_mov_b32_e32 v64, v2
	v_mov_b32_e32 v65, v2
	s_branch .LBB0_176
